# LayerNorm wave sums: last four xor-butterfly steps (8,4,2,1) via DPP adds with the same pairings instead of ds_bpermute round trips
# speedup vs baseline: 1.0080x; 1.0073x over previous
; DI float wave_sum(float v) { for (int o = 32; o > 0; o >>= 1) v += __shfl_xor(v, o); return v; }
; DI void phase_ln(const Params& p, int layer, const VBC& vc) {
;     ...
;         for (int j = 0; j < 4; ++j) { v[j] = *(const float4*)(xr + lane * 4 + 256 * j); s += v[j].x + v[j].y + v[j].z + v[j].w; }
;         const float mean = wave_sum(s) * (1.f / 1024.f);
;         float q = 0.f;
; #pragma unroll
;         for (int j = 0; j < 4; ++j) { v[j].x -= mean; v[j].y -= mean; v[j].z -= mean; v[j].w -= mean; q += v[j].x * v[j].x + v[j].y * v[j].y + v[j].z * v[j].z + v[j].w * v[j].w; }
;         const float rstd = rsqrtf(wave_sum(q) * (1.f / 1024.f) + LN_EPS);
;         const int r = row < NLAT ? (row >> 12) : 8;
;         const float* md = MOD + ((size_t)(layer + 1) * 9 + r) * 3072;
;         if (layer < DEPTH - 1 && lane == 0) ((float2*)(p.ws + OFF_STATS))[row] = make_float2(mean, rstd);
.Lln_nomd:
	s_waitcnt vmcnt(0)
	v_add_f32_e32 v142, v60, v64
	v_add_f32_e32 v143, v61, v65
	v_add_f32_e32 v144, v62, v66
	v_add_f32_e32 v145, v63, v67
	v_add_f32_e32 v142, v142, v68
	v_add_f32_e32 v143, v143, v69
	v_add_f32_e32 v144, v144, v70
	v_add_f32_e32 v145, v145, v71
	v_add_f32_e32 v142, v142, v72
	v_add_f32_e32 v143, v143, v73
	v_add_f32_e32 v144, v144, v74
	v_add_f32_e32 v145, v145, v75
	v_add_f32_e32 v142, v142, v143
	v_add_f32_e32 v144, v144, v145
	v_add_f32_e32 v19, v142, v144
	ds_bpermute_b32 v21, v9, v19
	s_waitcnt lgkmcnt(0)
	v_add_f32_e32 v19, v19, v21
	ds_bpermute_b32 v21, v46, v19
	s_waitcnt lgkmcnt(0)
	v_add_f32_e32 v19, v19, v21
	s_nop 1
	v_add_f32_dpp v19, v19, v19 row_ror:8 row_mask:0xf bank_mask:0xf
	s_nop 1
	v_add_f32_dpp v21, v19, v19 row_shl:4 row_mask:0xf bank_mask:0x5
	v_add_f32_dpp v21, v19, v19 row_shr:4 row_mask:0xf bank_mask:0xa
	s_nop 1
	v_add_f32_dpp v19, v21, v21 quad_perm:[2,3,0,1] row_mask:0xf bank_mask:0xf
	s_nop 1
	v_add_f32_dpp v19, v19, v19 quad_perm:[1,0,3,2] row_mask:0xf bank_mask:0xf
	v_mul_f32_e32 v140, 0x3a800000, v19
	v_sub_f32_e32 v60, v60, v140
	v_sub_f32_e32 v61, v61, v140
	v_sub_f32_e32 v62, v62, v140
	v_sub_f32_e32 v63, v63, v140
	v_sub_f32_e32 v64, v64, v140
	v_sub_f32_e32 v65, v65, v140
	v_sub_f32_e32 v66, v66, v140
	v_sub_f32_e32 v67, v67, v140
	v_sub_f32_e32 v68, v68, v140
	v_sub_f32_e32 v69, v69, v140
	v_sub_f32_e32 v70, v70, v140
	v_sub_f32_e32 v71, v71, v140
	v_sub_f32_e32 v72, v72, v140
	v_sub_f32_e32 v73, v73, v140
	v_sub_f32_e32 v74, v74, v140
	v_sub_f32_e32 v75, v75, v140
	v_mul_f32_e32 v142, v60, v60
	v_mul_f32_e32 v143, v61, v61
	v_mul_f32_e32 v144, v62, v62
	v_mul_f32_e32 v145, v63, v63
	v_fmac_f32_e32 v142, v64, v64
	v_fmac_f32_e32 v143, v65, v65
	v_fmac_f32_e32 v144, v66, v66
	v_fmac_f32_e32 v145, v67, v67
	v_fmac_f32_e32 v142, v68, v68
	v_fmac_f32_e32 v143, v69, v69
	v_fmac_f32_e32 v144, v70, v70
	v_fmac_f32_e32 v145, v71, v71
	v_fmac_f32_e32 v142, v72, v72
	v_fmac_f32_e32 v143, v73, v73
	v_fmac_f32_e32 v144, v74, v74
	v_fmac_f32_e32 v145, v75, v75
	v_add_f32_e32 v142, v142, v143
	v_add_f32_e32 v144, v144, v145
	v_add_f32_e32 v19, v142, v144
	ds_bpermute_b32 v21, v9, v19
	s_waitcnt lgkmcnt(0)
	v_add_f32_e32 v19, v19, v21
	ds_bpermute_b32 v21, v46, v19
	s_waitcnt lgkmcnt(0)
	v_add_f32_e32 v19, v19, v21
	s_nop 1
	v_add_f32_dpp v19, v19, v19 row_ror:8 row_mask:0xf bank_mask:0xf
	s_nop 1
	v_add_f32_dpp v21, v19, v19 row_shl:4 row_mask:0xf bank_mask:0x5
	v_add_f32_dpp v21, v19, v19 row_shr:4 row_mask:0xf bank_mask:0xa
	s_nop 1
	v_add_f32_dpp v19, v21, v21 quad_perm:[2,3,0,1] row_mask:0xf bank_mask:0xf
	s_nop 1
	v_add_f32_dpp v19, v19, v19 quad_perm:[1,0,3,2] row_mask:0xf bank_mask:0xf
	v_fmamk_f32 v2, v19, 0x3a800000, v229
	v_cmp_gt_f32_e32 vcc, s95, v2
	v_mul_f32_e32 v3, 0x4b800000, v2
	s_nop 0
	v_cndmask_b32_e32 v2, v2, v3, vcc
	v_rsq_f32_e32 v2, v2
	s_nop 0
	v_mul_f32_e32 v3, 0x45800000, v2
	v_cndmask_b32_e32 v141, v2, v3, vcc
	s_and_saveexec_b64 s[0:1], s[12:13]
	s_cbranch_execz .Lln_nostat
	v_lshl_add_u64 v[2:3], s[30:31], 0, v[14:15]
	v_add_co_u32_e32 v2, vcc, 0x1e423000, v2
	s_nop 1
	v_addc_co_u32_e32 v3, vcc, 0, v3, vcc
	global_store_dwordx2 v[2:3], v[140:141], off offset:512
